# GEMM main loops: leading wave half (waves 0-3) at static priority 1, trailing half at 0
# speedup vs baseline: 1.0019x; 1.0019x over previous
; #define PG8_STAGE(bufoff, gbase, voff) do { _Pragma("unroll") for (int _i = 0; _i < 2; ++_i) \
;         __builtin_amdgcn_global_load_lds((const unsigned*)((const char*)(gbase) + (voff)[_i]), (PG8_LAS unsigned*)(lds + (bufoff) + ldsw + _i * 8192), 16, 0, 0); } while (0)
; #define PG8_LDA(dst, b, h) do { _Pragma("unroll") for (int m = 0; m < 4; ++m) _Pragma("unroll") for (int k = 0; k < 2; ++k) dst[m][k] = *(const PG8_LAS bf16x8*)(lds + PG8_SA(b, h) + aoff + m * 2048 + k * 1024); } while (0)
; #define PG8_LDB(dst, b, h) do { _Pragma("unroll") for (int n = 0; n < 2; ++n) _Pragma("unroll") for (int k = 0; k < 2; ++k) dst[n][k] = *(const PG8_LAS bf16x8*)(lds + (SP2 ? PG8_SB(b, hw) + (h) * 4096 : PG8_SB(b, h)) + boff + n * 2048 + k * 1024); } while (0)
; #define PG8_WAIT_V(n) asm volatile("s_waitcnt vmcnt(" #n ")" ::: "memory")
; #define PG8_WAIT_L(n) asm volatile("s_waitcnt lgkmcnt(" #n ")" ::: "memory")
; #define PG8_BAR __builtin_amdgcn_s_barrier()
; #define PG8_SCHED __builtin_amdgcn_sched_barrier(0)
; template <class Epi, class Sched, bool ALIGN_EPI = false, bool SP2 = false, bool F8 = false>
; __device__ __forceinline__ void gemm_phase(PG8_LAS unsigned char* lds, const Gemm g, const Sched& S, const Epi& E, int wv) {
;     ...
;             const char* a1 = cA + (size_t)(t + 1) * kstep;
;             const char* a2 = last ? nA : cA + (size_t)(t + 2) * kstep; const char* b2 = last ? nB : cB + (size_t)(t + 2) * kstep;
;             const char* a3 = a2 + kstep; const char* b3 = b2 + kstep;
;             if (last && has_next) S.a_ready(nxt);
;             if constexpr (SP2) {
;             PG8_LDB(B0, 0, 0); PG8_LDB(B1, 0, 1); PG8_SCHED; PG8_LDA(At, 0, 0); PG8_STAGE(PG8_SA(1, 1), a1 + hstepA, voffA);
;             PG8_WAIT_V(8); PG8_WAIT_L(0); PG8_BAR; PG8_MMA(0, 0, At, B0); PG8_MMA(0, 1, At, B1); PG8_BAR; PG8_SCHED;
.LBB0_239:
	v_add_u32_e32 v149, s45, v146
	ds_read_b128 v[140:143], v149
	ds_read_b128 v[150:153], v149 offset:1024
	ds_read_b128 v[154:157], v149 offset:2048
	ds_read_b128 v[158:161], v149 offset:3072
	v_add_u32_e32 v149, s46, v146
	ds_read_b128 v[162:165], v149
	ds_read_b128 v[166:169], v149 offset:1024
	ds_read_b128 v[170:173], v149 offset:2048
	ds_read_b128 v[174:177], v149 offset:3072
	s_add_u32 s22, s20, 0xfff80080
	s_addc_u32 s23, s21, -1
	s_cmp_eq_u32 s61, 28
	s_cselect_b32 s25, s15, s23
	s_cselect_b32 s24, s57, s22
	s_cselect_b32 s23, s13, s60
	s_cselect_b32 s22, s58, s59
	v_lshl_add_u64 v[208:209], s[20:21], 0, v[136:137]
	s_add_i32 m0, s29, 0xc000
	ds_read_b128 v[178:181], v148
	ds_read_b128 v[182:185], v148 offset:1024
	ds_read_b128 v[186:189], v148 offset:2048
	ds_read_b128 v[190:193], v148 offset:3072
	ds_read_b128 v[194:197], v148 offset:4096
	ds_read_b128 v[198:201], v148 offset:5120
	ds_read_b128 v[202:205], v148 offset:6144
	ds_read_b128 v[214:217], v148 offset:7168
	global_load_lds_dwordx4 v[208:209], off
	v_lshl_add_u64 v[208:209], s[20:21], 0, v[138:139]
	s_add_i32 m0, s29, 0xe000
	s_nop 0
	global_load_lds_dwordx4 v[208:209], off
	s_waitcnt vmcnt(8)
	s_waitcnt lgkmcnt(0)
	s_barrier
	s_cmp_ge_u32 s88, 4
	s_cbranch_scc1 .Lprio_lead_1
	s_setprio 1

; #define PG8_STAGE(bufoff, gbase, voff) do { _Pragma("unroll") for (int _i = 0; _i < 2; ++_i) \
;         __builtin_amdgcn_global_load_lds((const unsigned*)((const char*)(gbase) + (voff)[_i]), (PG8_LAS unsigned*)(lds + (bufoff) + ldsw + _i * 8192), 16, 0, 0); } while (0)
; #define PG8_LDA(dst, b, h) do { _Pragma("unroll") for (int m = 0; m < 4; ++m) _Pragma("unroll") for (int k = 0; k < 2; ++k) dst[m][k] = *(const PG8_LAS bf16x8*)(lds + PG8_SA(b, h) + aoff + m * 2048 + k * 1024); } while (0)
; #define PG8_LDB(dst, b, h) do { _Pragma("unroll") for (int n = 0; n < 2; ++n) _Pragma("unroll") for (int k = 0; k < 2; ++k) dst[n][k] = *(const PG8_LAS bf16x8*)(lds + (SP2 ? PG8_SB(b, hw) + (h) * 4096 : PG8_SB(b, h)) + boff + n * 2048 + k * 1024); } while (0)
; #define PG8_WAIT_V(n) asm volatile("s_waitcnt vmcnt(" #n ")" ::: "memory")
; #define PG8_WAIT_L(n) asm volatile("s_waitcnt lgkmcnt(" #n ")" ::: "memory")
; #define PG8_BAR __builtin_amdgcn_s_barrier()
; #define PG8_SCHED __builtin_amdgcn_sched_barrier(0)
; template <class Epi, class Sched, bool ALIGN_EPI = false, bool SP2 = false, bool F8 = false>
; __device__ __forceinline__ void gemm_phase(PG8_LAS unsigned char* lds, const Gemm g, const Sched& S, const Epi& E, int wv) {
;     ...
;             const bool last = (t == nt - 2);
;             const char* a1 = cA + (size_t)(t + 1) * kstep;
;             const char* a2 = last ? nA : cA + (size_t)(t + 2) * kstep; const char* b2 = last ? nB : cB + (size_t)(t + 2) * kstep;
;             const char* a3 = a2 + kstep; const char* b3 = b2 + kstep;
;             if (last && has_next) S.a_ready(nxt);
;             if constexpr (SP2) {
;             PG8_LDB(B0, 0, 0); PG8_LDB(B1, 0, 1); PG8_SCHED; PG8_LDA(At, 0, 0); PG8_STAGE(PG8_SA(1, 1), a1 + hstepA, voffA);
;             PG8_WAIT_V(8); PG8_WAIT_L(0); PG8_BAR; PG8_MMA(0, 0, At, B0); PG8_MMA(0, 1, At, B1); PG8_BAR; PG8_SCHED;
.LBB0_286:
	v_add_u32_e32 v0, s59, v181
	v_add_u32_e32 v4, s60, v181
	ds_read_b128 v[24:27], v0
	ds_read_b128 v[28:31], v0 offset:1024
	ds_read_b128 v[16:19], v0 offset:2048
	ds_read_b128 v[20:23], v0 offset:3072
	ds_read_b128 v[8:11], v4
	ds_read_b128 v[12:15], v4 offset:1024
	ds_read_b128 v[0:3], v4 offset:2048
	ds_read_b128 v[4:7], v4 offset:3072
	s_add_u32 s28, s26, 0xfffc0080
	s_addc_u32 s29, s27, -1
	s_cmp_eq_u32 s71, 12
	s_cselect_b32 s31, s13, s29
	s_cselect_b32 s30, s17, s28
	s_cselect_b32 s29, s15, s70
	s_cselect_b32 s28, s67, s69
	v_lshl_add_u64 v[200:201], s[26:27], 0, v[168:169]
	s_add_i32 m0, s19, 0xc000
	ds_read_b128 v[172:175], v183
	ds_read_b128 v[176:179], v183 offset:1024
	ds_read_b128 v[184:187], v183 offset:2048
	ds_read_b128 v[188:191], v183 offset:3072
	ds_read_b128 v[192:195], v183 offset:4096
	ds_read_b128 v[196:199], v183 offset:5120
	ds_read_b128 v[214:217], v183 offset:6144
	ds_read_b128 v[218:221], v183 offset:7168
	global_load_lds_dwordx4 v[200:201], off
	v_lshl_add_u64 v[200:201], s[26:27], 0, v[170:171]
	s_add_i32 m0, s19, 0xe000
	s_nop 0
	global_load_lds_dwordx4 v[200:201], off
	s_waitcnt vmcnt(8)
	s_waitcnt lgkmcnt(0)
	s_barrier
	s_cmp_ge_u32 s88, 4
	s_cbranch_scc1 .Lprio_lead_2
	s_setprio 1

; #define PG8_STAGE(bufoff, gbase, voff) do { _Pragma("unroll") for (int _i = 0; _i < 2; ++_i) \
;         __builtin_amdgcn_global_load_lds((const unsigned*)((const char*)(gbase) + (voff)[_i]), (PG8_LAS unsigned*)(lds + (bufoff) + ldsw + _i * 8192), 16, 0, 0); } while (0)
; #define PG8_LDA(dst, b, h) do { _Pragma("unroll") for (int m = 0; m < 4; ++m) _Pragma("unroll") for (int k = 0; k < 2; ++k) dst[m][k] = *(const PG8_LAS bf16x8*)(lds + PG8_SA(b, h) + aoff + m * 2048 + k * 1024); } while (0)
; #define PG8_LDB(dst, b, h) do { _Pragma("unroll") for (int n = 0; n < 2; ++n) _Pragma("unroll") for (int k = 0; k < 2; ++k) dst[n][k] = *(const PG8_LAS bf16x8*)(lds + (SP2 ? PG8_SB(b, hw) + (h) * 4096 : PG8_SB(b, h)) + boff + n * 2048 + k * 1024); } while (0)
; #define PG8_WAIT_V(n) asm volatile("s_waitcnt vmcnt(" #n ")" ::: "memory")
; #define PG8_WAIT_L(n) asm volatile("s_waitcnt lgkmcnt(" #n ")" ::: "memory")
; #define PG8_BAR __builtin_amdgcn_s_barrier()
; #define PG8_SCHED __builtin_amdgcn_sched_barrier(0)
; template <class Epi, class Sched, bool ALIGN_EPI = false, bool SP2 = false, bool F8 = false>
; __device__ __forceinline__ void gemm_phase(PG8_LAS unsigned char* lds, const Gemm g, const Sched& S, const Epi& E, int wv) {
;     ...
;             const bool last = (t == nt - 2);
;             const char* a1 = cA + (size_t)(t + 1) * kstep;
;             const char* a2 = last ? nA : cA + (size_t)(t + 2) * kstep; const char* b2 = last ? nB : cB + (size_t)(t + 2) * kstep;
;             const char* a3 = a2 + kstep; const char* b3 = b2 + kstep;
;             if (last && has_next) S.a_ready(nxt);
;             if constexpr (SP2) {
;             PG8_LDB(B0, 0, 0); PG8_LDB(B1, 0, 1); PG8_SCHED; PG8_LDA(At, 0, 0); PG8_STAGE(PG8_SA(1, 1), a1 + hstepA, voffA);
;             PG8_WAIT_V(8); PG8_WAIT_L(0); PG8_BAR; PG8_MMA(0, 0, At, B0); PG8_MMA(0, 1, At, B1); PG8_BAR; PG8_SCHED;
.LBB0_638:
	v_add_u32_e32 v12, s57, v189
	v_add_u32_e32 v28, s58, v189
	s_add_u32 s22, s18, s20
	ds_read_b128 v[0:3], v12
	ds_read_b128 v[4:7], v12 offset:1024
	ds_read_b128 v[8:11], v12 offset:2048
	ds_read_b128 v[12:15], v12 offset:3072
	ds_read_b128 v[16:19], v28
	ds_read_b128 v[20:23], v28 offset:1024
	ds_read_b128 v[24:27], v28 offset:2048
	ds_read_b128 v[28:31], v28 offset:3072
	s_addc_u32 s23, s19, s21
	s_add_u32 s22, s22, 0x100
	s_addc_u32 s23, s23, 0
	s_add_u32 s67, s71, s20
	s_addc_u32 s74, s72, s21
	s_cmpk_eq_i32 s20, 0x700
	s_cselect_b32 s25, s13, s23
	s_cselect_b32 s24, s63, s22
	s_cselect_b32 s23, s65, s74
	s_cselect_b32 s22, s68, s67
	v_lshl_add_u64 v[130:131], v[176:177], 0, s[20:21]
	s_add_i32 m0, s34, 0xc000
	ds_read_b128 v[192:195], v191
	ds_read_b128 v[196:199], v191 offset:1024
	ds_read_b128 v[214:217], v191 offset:2048
	ds_read_b128 v[218:221], v191 offset:3072
	ds_read_b128 v[222:225], v191 offset:4096
	ds_read_b128 v[226:229], v191 offset:5120
	ds_read_b128 v[230:233], v191 offset:6144
	ds_read_b128 v[234:237], v191 offset:7168
	global_load_lds_dwordx4 v[130:131], off
	v_lshl_add_u64 v[130:131], v[178:179], 0, s[20:21]
	s_add_i32 m0, s34, 0xe000
	s_nop 0
	global_load_lds_dwordx4 v[130:131], off
	s_waitcnt vmcnt(8)
	s_waitcnt lgkmcnt(0)
	s_barrier
	s_cmp_ge_u32 s88, 4
	s_cbranch_scc1 .Lprio_lead_3
	s_setprio 1

; #define PG8_STAGE(bufoff, gbase, voff) do { _Pragma("unroll") for (int _i = 0; _i < 2; ++_i) \
;         __builtin_amdgcn_global_load_lds((const unsigned*)((const char*)(gbase) + (voff)[_i]), (PG8_LAS unsigned*)(lds + (bufoff) + ldsw + _i * 8192), 16, 0, 0); } while (0)
; #define PG8_LDA(dst, b, h) do { _Pragma("unroll") for (int m = 0; m < 4; ++m) _Pragma("unroll") for (int k = 0; k < 2; ++k) dst[m][k] = *(const PG8_LAS bf16x8*)(lds + PG8_SA(b, h) + aoff + m * 2048 + k * 1024); } while (0)
; #define PG8_LDB(dst, b, h) do { _Pragma("unroll") for (int n = 0; n < 2; ++n) _Pragma("unroll") for (int k = 0; k < 2; ++k) dst[n][k] = *(const PG8_LAS bf16x8*)(lds + (SP2 ? PG8_SB(b, hw) + (h) * 4096 : PG8_SB(b, h)) + boff + n * 2048 + k * 1024); } while (0)
; #define PG8_WAIT_V(n) asm volatile("s_waitcnt vmcnt(" #n ")" ::: "memory")
; #define PG8_WAIT_L(n) asm volatile("s_waitcnt lgkmcnt(" #n ")" ::: "memory")
; #define PG8_BAR __builtin_amdgcn_s_barrier()
; #define PG8_SCHED __builtin_amdgcn_sched_barrier(0)
; template <class Epi, class Sched, bool ALIGN_EPI = false, bool SP2 = false, bool F8 = false>
; __device__ __forceinline__ void gemm_phase(PG8_LAS unsigned char* lds, const Gemm g, const Sched& S, const Epi& E, int wv) {
;     ...
;             const bool last = (t == nt - 2);
;             const char* a1 = cA + (size_t)(t + 1) * kstep;
;             const char* a2 = last ? nA : cA + (size_t)(t + 2) * kstep; const char* b2 = last ? nB : cB + (size_t)(t + 2) * kstep;
;             const char* a3 = a2 + kstep; const char* b3 = b2 + kstep;
;             if (last && has_next) S.a_ready(nxt);
;             if constexpr (SP2) {
;             PG8_LDB(B0, 0, 0); PG8_LDB(B1, 0, 1); PG8_SCHED; PG8_LDA(At, 0, 0); PG8_STAGE(PG8_SA(1, 1), a1 + hstepA, voffA);
;             PG8_WAIT_V(8); PG8_WAIT_L(0); PG8_BAR; PG8_MMA(0, 0, At, B0); PG8_MMA(0, 1, At, B1); PG8_BAR; PG8_SCHED;
.LBB0_711:
	v_add_u32_e32 v0, s48, v181
	v_add_u32_e32 v4, s49, v181
	ds_read_b128 v[24:27], v0
	ds_read_b128 v[28:31], v0 offset:1024
	ds_read_b128 v[16:19], v0 offset:2048
	ds_read_b128 v[20:23], v0 offset:3072
	ds_read_b128 v[8:11], v4
	ds_read_b128 v[12:15], v4 offset:1024
	ds_read_b128 v[0:3], v4 offset:2048
	ds_read_b128 v[4:7], v4 offset:3072
	s_add_u32 s20, s18, 0xfffc0080
	s_addc_u32 s21, s19, -1
	s_cmp_eq_u32 s61, 12
	s_cselect_b32 s23, s9, s21
	s_cselect_b32 s22, s15, s20
	s_cselect_b32 s21, s7, s60
	s_cselect_b32 s20, s58, s59
	v_lshl_add_u64 v[200:201], s[18:19], 0, v[168:169]
	s_add_i32 m0, s17, 0xc000
	ds_read_b128 v[172:175], v183
	ds_read_b128 v[176:179], v183 offset:1024
	ds_read_b128 v[184:187], v183 offset:2048
	ds_read_b128 v[188:191], v183 offset:3072
	ds_read_b128 v[192:195], v183 offset:4096
	ds_read_b128 v[196:199], v183 offset:5120
	ds_read_b128 v[214:217], v183 offset:6144
	ds_read_b128 v[218:221], v183 offset:7168
	global_load_lds_dwordx4 v[200:201], off
	v_lshl_add_u64 v[200:201], s[18:19], 0, v[170:171]
	s_add_i32 m0, s17, 0xe000
	s_nop 0
	global_load_lds_dwordx4 v[200:201], off
	s_waitcnt vmcnt(8)
	s_waitcnt lgkmcnt(0)
	s_barrier
	s_cmp_ge_u32 s88, 4
	s_cbranch_scc1 .Lprio_lead_4
	s_setprio 1

; #define PG8_STAGE(bufoff, gbase, voff) do { _Pragma("unroll") for (int _i = 0; _i < 2; ++_i) \
;         __builtin_amdgcn_global_load_lds((const unsigned*)((const char*)(gbase) + (voff)[_i]), (PG8_LAS unsigned*)(lds + (bufoff) + ldsw + _i * 8192), 16, 0, 0); } while (0)
; #define PG8_LDA(dst, b, h) do { _Pragma("unroll") for (int m = 0; m < 4; ++m) _Pragma("unroll") for (int k = 0; k < 2; ++k) dst[m][k] = *(const PG8_LAS bf16x8*)(lds + PG8_SA(b, h) + aoff + m * 2048 + k * 1024); } while (0)
; #define PG8_LDB(dst, b, h) do { _Pragma("unroll") for (int n = 0; n < 2; ++n) _Pragma("unroll") for (int k = 0; k < 2; ++k) dst[n][k] = *(const PG8_LAS bf16x8*)(lds + (SP2 ? PG8_SB(b, hw) + (h) * 4096 : PG8_SB(b, h)) + boff + n * 2048 + k * 1024); } while (0)
; #define PG8_WAIT_V(n) asm volatile("s_waitcnt vmcnt(" #n ")" ::: "memory")
; #define PG8_WAIT_L(n) asm volatile("s_waitcnt lgkmcnt(" #n ")" ::: "memory")
; #define PG8_BAR __builtin_amdgcn_s_barrier()
; #define PG8_SCHED __builtin_amdgcn_sched_barrier(0)
; template <class Epi, class Sched, bool ALIGN_EPI = false, bool SP2 = false, bool F8 = false>
; __device__ __forceinline__ void gemm_phase(PG8_LAS unsigned char* lds, const Gemm g, const Sched& S, const Epi& E, int wv) {
;     ...
;             const bool last = (t == nt - 2);
;             const char* a1 = cA + (size_t)(t + 1) * kstep;
;             const char* a2 = last ? nA : cA + (size_t)(t + 2) * kstep; const char* b2 = last ? nB : cB + (size_t)(t + 2) * kstep;
;             const char* a3 = a2 + kstep; const char* b3 = b2 + kstep;
;             if (last && has_next) S.a_ready(nxt);
;             if constexpr (SP2) {
;             PG8_LDB(B0, 0, 0); PG8_LDB(B1, 0, 1); PG8_SCHED; PG8_LDA(At, 0, 0); PG8_STAGE(PG8_SA(1, 1), a1 + hstepA, voffA);
;             PG8_WAIT_V(8); PG8_WAIT_L(0); PG8_BAR; PG8_MMA(0, 0, At, B0); PG8_MMA(0, 1, At, B1); PG8_BAR; PG8_SCHED;
.LBB0_846:
	v_add_u32_e32 v140, s47, v143
	ds_read_b128 v[146:149], v140
	ds_read_b128 v[150:153], v140 offset:1024
	ds_read_b128 v[154:157], v140 offset:2048
	ds_read_b128 v[158:161], v140 offset:3072
	v_add_u32_e32 v140, s48, v143
	ds_read_b128 v[162:165], v140
	ds_read_b128 v[166:169], v140 offset:1024
	ds_read_b128 v[170:173], v140 offset:2048
	ds_read_b128 v[174:177], v140 offset:3072
	s_add_u32 s22, s20, 0xfff80080
	s_addc_u32 s23, s21, -1
	s_cmp_eq_u32 s61, 28
	s_cselect_b32 s25, s11, s23
	s_cselect_b32 s24, s57, s22
	s_cselect_b32 s23, s9, s60
	s_cselect_b32 s22, s58, s59
	v_lshl_add_u64 v[140:141], s[20:21], 0, v[136:137]
	s_add_i32 m0, s13, 0xc000
	ds_read_b128 v[178:181], v145
	ds_read_b128 v[182:185], v145 offset:1024
	ds_read_b128 v[186:189], v145 offset:2048
	ds_read_b128 v[190:193], v145 offset:3072
	ds_read_b128 v[194:197], v145 offset:4096
	ds_read_b128 v[198:201], v145 offset:5120
	ds_read_b128 v[202:205], v145 offset:6144
	ds_read_b128 v[208:211], v145 offset:7168
	global_load_lds_dwordx4 v[140:141], off
	v_lshl_add_u64 v[140:141], s[20:21], 0, v[138:139]
	s_add_i32 m0, s13, 0xe000
	s_nop 0
	global_load_lds_dwordx4 v[140:141], off
	s_waitcnt vmcnt(8)
	s_waitcnt lgkmcnt(0)
	s_barrier
	s_cmp_ge_u32 s88, 4
	s_cbranch_scc1 .Lprio_lead_5
	s_setprio 1
